# v084 + NA DMA source-address VALU moved into the DMA path (skipped on clamped rows)
# speedup vs baseline: 1.0015x; 1.0015x over previous
.LBB0_235:
	s_mul_hi_u32 s11, s8, 0x24924925
	s_sub_i32 s74, s8, s11
	s_lshr_b32 s74, s74, 1
	s_add_i32 s74, s74, s11
	s_lshr_b32 s11, s74, 2
	s_add_i32 s74, s6, s87
	s_add_i32 s76, s74, 8
	s_add_i32 s74, s87, 17
	s_cmp_gt_i32 s74, s95
	s_cselect_b32 s100, 1, 0
	s_min_i32 s74, s74, s95
	s_mul_i32 s11, s11, 0x1c000
	s_sub_i32 s11, s9, s11
	s_sub_i32 s101, s95, s87
	s_addk_i32 s101, 0xfff4
	s_cmp_gt_i32 s101, 3
	s_cbranch_scc1 .Lna_w8
	s_cmp_eq_u32 s101, 3
	s_cbranch_scc1 .Lna_w6
	s_cmp_eq_u32 s101, 2
	s_cbranch_scc1 .Lna_w4
	s_cmp_eq_u32 s101, 1
	s_cbranch_scc1 .Lna_w2
	s_waitcnt vmcnt(0) lgkmcnt(0)
	s_branch .Lna_wj

.Lna_wj:
	s_barrier
	s_cmp_lg_u32 s100, 0
	s_cbranch_scc1 .Lna_nodma
	v_add_u32_e32 v66, s74, v65
	v_lshlrev_b32_e32 v68, 6, v66
	v_add_u32_e32 v66, v68, v141
	v_ashrrev_i32_e32 v67, 31, v66
	v_or_b32_e32 v68, v68, v145
	v_lshlrev_b64 v[66:67], 11, v[66:67]
	v_ashrrev_i32_e32 v69, 31, v68
	s_add_i32 s11, s11, 0
	v_lshl_add_u64 v[66:67], v[150:151], 0, v[66:67]
	v_lshlrev_b64 v[68:69], 11, v[68:69]
	s_add_i32 s74, s11, 0x14000
	s_add_i32 s11, s11, 0x16000
	v_lshl_add_u64 v[68:69], v[152:153], 0, v[68:69]
	s_mov_b32 s75, m0
	s_mov_b32 m0, s74
	s_nop 0
	global_load_lds_dwordx4 v[66:67], off
	s_mov_b32 m0, s11
	s_nop 0
	global_load_lds_dwordx4 v[68:69], off
	s_mov_b32 m0, s75
